# x->bf16 prologue rows in pairs with two pairs of loads in flight; sample attention's k/v/gain loads issued together
# baseline (speedup 1.0000x reference)
; __device__ __forceinline__ unsigned pk2(float lo, float hi) { return pg8::cvt_pk_bf16(lo, hi); }
; __device__ __forceinline__ float wave_sum(float v) {
; #pragma unroll
;     for (int o = 1; o < 64; o <<= 1) v += __shfl_xor(v, o);
;     return v;
; }
; __device__ __forceinline__ void prologue(const Args& a, LAS unsigned char* lds, int tid, int wave, int lane) {
;     ...
;     float* ss = (float*)(ws + WS_SS); bf16_t* XB = (bf16_t*)(ws + WS_A);
;     for (int m = gw; m < MTOK; m += NGW) {
;         const float* src = (m < NTOK_P) ? a.in[I_XP] + (size_t)m * DM : a.in[I_XS] + (size_t)(m - NTOK_P) * DM;
;         f32x4 v[4]; float s = 0.f;
; #pragma unroll
;         for (int j = 0; j < 4; ++j) { v[j] = __builtin_nontemporal_load((const f32x4*)src + lane + 64 * j); s += (v[j][0] * v[j][0] + v[j][1] * v[j][1]) + (v[j][2] * v[j][2] + v[j][3] * v[j][3]); }
;         s = wave_sum(s);
; #pragma unroll
;         for (int j = 0; j < 4; ++j) { u32x2 w; w.x = pk2(v[j][0], v[j][1]); w.y = pk2(v[j][2], v[j][3]); *((u32x2*)(XB + (size_t)m * DM) + lane + 64 * j) = w; }
;         if (lane == 0) ss[m] = s;
;     }
.LBB0_129:
	s_lshl_b32 s62, s2, 3
	s_add_i32 s0, s94, s62
	s_lshl_b32 s66, s34, 3
	s_add_u32 s88, s70, 0x100000
	s_addc_u32 s89, s71, 0
	s_add_u32 s30, s70, 0x3900000
	s_addc_u32 s31, s71, 0
	s_cmpk_gt_i32 s0, 0x41ff
	s_waitcnt vmcnt(5)
	v_mbcnt_lo_u32_b32 v8, -1, 0
	s_cbranch_scc1 .LBB0_136
	v_mbcnt_hi_u32_b32 v0, -1, v8
	v_and_b32_e32 v2, 64, v0
	v_add_u32_e32 v2, 64, v2
	v_xor_b32_e32 v3, 1, v0
	v_cmp_lt_i32_e32 vcc, v3, v2
	s_ashr_i32 s1, s0, 31
	s_ashr_i32 s67, s66, 31
	v_cndmask_b32_e32 v3, v0, v3, vcc
	v_lshlrev_b32_e32 v4, 2, v3
	v_xor_b32_e32 v3, 2, v0
	v_cmp_lt_i32_e32 vcc, v3, v2
	s_lshl_b64 s[6:7], s[0:1], 12
	v_readlane_b32 s8, v252, 0
	v_cndmask_b32_e32 v3, v0, v3, vcc
	v_lshlrev_b32_e32 v5, 2, v3
	v_xor_b32_e32 v3, 4, v0
	v_cmp_lt_i32_e32 vcc, v3, v2
	v_mov_b32_e32 v1, 0
	v_readlane_b32 s9, v252, 1
	v_cndmask_b32_e32 v3, v0, v3, vcc
	v_lshlrev_b32_e32 v6, 2, v3
	v_xor_b32_e32 v3, 8, v0
	v_cmp_lt_i32_e32 vcc, v3, v2
	s_add_u32 s6, s8, s6
	s_mov_b32 s5, 0
	v_cndmask_b32_e32 v3, v0, v3, vcc
	v_lshlrev_b32_e32 v7, 2, v3
	v_xor_b32_e32 v3, 16, v0
	v_cmp_lt_i32_e32 vcc, v3, v2
	s_addc_u32 s7, s9, s7
	s_lshl_b64 s[8:9], s[66:67], 12
	v_cndmask_b32_e32 v3, v0, v3, vcc
	v_lshlrev_b32_e32 v9, 2, v3
	v_xor_b32_e32 v3, 32, v0
	v_cmp_lt_i32_e32 vcc, v3, v2
	v_readlane_b32 s10, v252, 2
	v_readlane_b32 s11, v252, 3
	v_cndmask_b32_e32 v0, v0, v3, vcc
	v_lshlrev_b32_e32 v10, 2, v0
	v_lshlrev_b32_e32 v0, 3, v32
	v_lshl_add_u64 v[2:3], s[30:31], 0, v[0:1]
	v_cmp_eq_u32_e32 vcc, 0, v32
	v_lshlrev_b32_e32 v0, 4, v32
	v_readlane_b32 s12, v252, 4
	v_readlane_b32 s13, v252, 5
	v_readlane_b32 s14, v252, 6
	v_readlane_b32 s15, v252, 7
	v_readlane_b32 s16, v252, 8
	v_readlane_b32 s17, v252, 9
	v_readlane_b32 s18, v252, 10
	v_readlane_b32 s19, v252, 11
	v_readlane_b32 s20, v252, 12
	v_readlane_b32 s21, v252, 13
	v_readlane_b32 s22, v252, 14
	v_readlane_b32 s23, v252, 15
	s_mul_i32 s10, s66, 7
	s_add_i32 s10, s10, s0
	s_cmpk_lt_i32 s10, 0x4000
	s_cbranch_scc0 .LBB0_132
	s_add_u32 s12, s6, s8
	s_addc_u32 s13, s7, s9
	s_add_u32 s14, s12, s8
	s_addc_u32 s15, s13, s9
	s_add_u32 s16, s14, s8
	s_addc_u32 s17, s15, s9
	s_add_u32 s18, s16, s8
	s_addc_u32 s19, s17, s9
	s_add_u32 s20, s18, s8
	s_addc_u32 s21, s19, s9
	s_add_u32 s22, s20, s8
	s_addc_u32 s23, s21, s9
	s_add_u32 s24, s22, s8
	s_addc_u32 s25, s23, s9
	global_load_dwordx4 v[72:75], v0, s[6:7] nt
	global_load_dwordx4 v[76:79], v0, s[6:7] offset:1024 nt
	global_load_dwordx4 v[80:83], v0, s[6:7] offset:2048 nt
	global_load_dwordx4 v[84:87], v0, s[6:7] offset:3072 nt
	global_load_dwordx4 v[88:91], v0, s[12:13] nt
	global_load_dwordx4 v[92:95], v0, s[12:13] offset:1024 nt
	global_load_dwordx4 v[96:99], v0, s[12:13] offset:2048 nt
	global_load_dwordx4 v[100:103], v0, s[12:13] offset:3072 nt
	global_load_dwordx4 v[104:107], v0, s[14:15] nt
	global_load_dwordx4 v[108:111], v0, s[14:15] offset:1024 nt
	global_load_dwordx4 v[112:115], v0, s[14:15] offset:2048 nt
	global_load_dwordx4 v[116:119], v0, s[14:15] offset:3072 nt
	global_load_dwordx4 v[120:123], v0, s[16:17] nt
	global_load_dwordx4 v[124:127], v0, s[16:17] offset:1024 nt
	global_load_dwordx4 v[128:131], v0, s[16:17] offset:2048 nt
	global_load_dwordx4 v[132:135], v0, s[16:17] offset:3072 nt
	s_waitcnt vmcnt(8)
	v_mul_f32_e32 v136, v73, v73
	v_mul_f32_e32 v137, v75, v75
	v_mul_f32_e32 v138, v77, v77
	v_mul_f32_e32 v139, v79, v79
	v_mul_f32_e32 v140, v81, v81
	v_mul_f32_e32 v141, v83, v83
	v_mul_f32_e32 v142, v85, v85
	v_mul_f32_e32 v143, v87, v87
	v_fmac_f32_e32 v136, v72, v72
	v_fmac_f32_e32 v137, v74, v74
	v_fmac_f32_e32 v138, v76, v76
	v_fmac_f32_e32 v139, v78, v78
	v_fmac_f32_e32 v140, v80, v80
	v_fmac_f32_e32 v141, v82, v82
	v_fmac_f32_e32 v142, v84, v84
	v_fmac_f32_e32 v143, v86, v86
	v_add_f32_e32 v136, v136, v137
	v_add_f32_e32 v138, v138, v139
	v_add_f32_e32 v140, v140, v141
	v_add_f32_e32 v142, v142, v143
	v_add_f32_e32 v168, v136, v138
	v_add_f32_e32 v168, v168, v140
	v_add_f32_e32 v168, v168, v142
	v_mul_f32_e32 v144, v89, v89
	v_mul_f32_e32 v145, v91, v91
	v_mul_f32_e32 v146, v93, v93
	v_mul_f32_e32 v147, v95, v95
	v_mul_f32_e32 v148, v97, v97
	v_mul_f32_e32 v149, v99, v99
	v_mul_f32_e32 v150, v101, v101
	v_mul_f32_e32 v151, v103, v103
	v_fmac_f32_e32 v144, v88, v88
	v_fmac_f32_e32 v145, v90, v90
	v_fmac_f32_e32 v146, v92, v92
	v_fmac_f32_e32 v147, v94, v94
	v_fmac_f32_e32 v148, v96, v96
	v_fmac_f32_e32 v149, v98, v98
	v_fmac_f32_e32 v150, v100, v100
	v_fmac_f32_e32 v151, v102, v102
	v_add_f32_e32 v144, v144, v145
	v_add_f32_e32 v146, v146, v147
	v_add_f32_e32 v148, v148, v149
	v_add_f32_e32 v150, v150, v151
	v_add_f32_e32 v169, v144, v146
	v_add_f32_e32 v169, v169, v148
	v_add_f32_e32 v169, v169, v150
	ds_bpermute_b32 v172, v4, v168
	ds_bpermute_b32 v173, v4, v169
	s_waitcnt lgkmcnt(0)
	v_add_f32_e32 v168, v168, v172
	v_add_f32_e32 v169, v169, v173
	ds_bpermute_b32 v172, v5, v168
	ds_bpermute_b32 v173, v5, v169
	s_waitcnt lgkmcnt(0)
	v_add_f32_e32 v168, v168, v172
	v_add_f32_e32 v169, v169, v173
	ds_bpermute_b32 v172, v6, v168
	ds_bpermute_b32 v173, v6, v169
	s_waitcnt lgkmcnt(0)
	v_add_f32_e32 v168, v168, v172
	v_add_f32_e32 v169, v169, v173
	ds_bpermute_b32 v172, v7, v168
	ds_bpermute_b32 v173, v7, v169
	s_waitcnt lgkmcnt(0)
	v_add_f32_e32 v168, v168, v172
	v_add_f32_e32 v169, v169, v173
	ds_bpermute_b32 v172, v9, v168
	ds_bpermute_b32 v173, v9, v169
	s_waitcnt lgkmcnt(0)
	v_add_f32_e32 v168, v168, v172
	v_add_f32_e32 v169, v169, v173
	ds_bpermute_b32 v172, v10, v168
	ds_bpermute_b32 v173, v10, v169
	s_waitcnt lgkmcnt(0)
; __device__ __forceinline__ unsigned pk2(float lo, float hi) { return pg8::cvt_pk_bf16(lo, hi); }
; __device__ __forceinline__ float wave_sum(float v) {
; #pragma unroll
;     for (int o = 1; o < 64; o <<= 1) v += __shfl_xor(v, o);
;     return v;
; }
; __device__ __forceinline__ void prologue(const Args& a, LAS unsigned char* lds, int tid, int wave, int lane) {
;     ...
;     float* ss = (float*)(ws + WS_SS); bf16_t* XB = (bf16_t*)(ws + WS_A);
;     for (int m = gw; m < MTOK; m += NGW) {
;         const float* src = (m < NTOK_P) ? a.in[I_XP] + (size_t)m * DM : a.in[I_XS] + (size_t)(m - NTOK_P) * DM;
;         f32x4 v[4]; float s = 0.f;
; #pragma unroll
;         for (int j = 0; j < 4; ++j) { v[j] = __builtin_nontemporal_load((const f32x4*)src + lane + 64 * j); s += (v[j][0] * v[j][0] + v[j][1] * v[j][1]) + (v[j][2] * v[j][2] + v[j][3] * v[j][3]); }
;         s = wave_sum(s);
; #pragma unroll
;         for (int j = 0; j < 4; ++j) { u32x2 w; w.x = pk2(v[j][0], v[j][1]); w.y = pk2(v[j][2], v[j][3]); *((u32x2*)(XB + (size_t)m * DM) + lane + 64 * j) = w; }
;         if (lane == 0) ss[m] = s;
;     }
	v_add_f32_e32 v168, v168, v172
	v_add_f32_e32 v169, v169, v173
	v_cvt_pk_bf16_f32 v72, v72, v73
	v_cvt_pk_bf16_f32 v73, v74, v75
	v_cvt_pk_bf16_f32 v76, v76, v77
	v_cvt_pk_bf16_f32 v77, v78, v79
	v_cvt_pk_bf16_f32 v80, v80, v81
	v_cvt_pk_bf16_f32 v81, v82, v83
	v_cvt_pk_bf16_f32 v84, v84, v85
	v_cvt_pk_bf16_f32 v85, v86, v87
	s_mul_i32 s10, s66, 0
	s_add_i32 s10, s10, s0
	s_lshl_b32 s26, s10, 2
	s_lshl_b32 s10, s10, 11
	s_mov_b32 s11, 0
	v_lshl_add_u64 v[176:177], v[2:3], 0, s[10:11]
	global_store_dwordx2 v[176:177], v[72:73], off
	global_store_dwordx2 v[176:177], v[76:77], off offset:512
	global_store_dwordx2 v[176:177], v[80:81], off offset:1024
	global_store_dwordx2 v[176:177], v[84:85], off offset:1536
	s_add_u32 s26, s88, s26
	s_addc_u32 s27, s89, 0
	s_and_saveexec_b64 s[98:99], vcc
	global_store_dword v1, v168, s[26:27]
	s_or_b64 exec, exec, s[98:99]
	v_cvt_pk_bf16_f32 v88, v88, v89
	v_cvt_pk_bf16_f32 v89, v90, v91
	v_cvt_pk_bf16_f32 v92, v92, v93
	v_cvt_pk_bf16_f32 v93, v94, v95
	v_cvt_pk_bf16_f32 v96, v96, v97
	v_cvt_pk_bf16_f32 v97, v98, v99
	v_cvt_pk_bf16_f32 v100, v100, v101
	v_cvt_pk_bf16_f32 v101, v102, v103
	s_mul_i32 s10, s66, 1
	s_add_i32 s10, s10, s0
	s_lshl_b32 s26, s10, 2
	s_lshl_b32 s10, s10, 11
	s_mov_b32 s11, 0
	v_lshl_add_u64 v[176:177], v[2:3], 0, s[10:11]
	global_store_dwordx2 v[176:177], v[88:89], off
	global_store_dwordx2 v[176:177], v[92:93], off offset:512
	global_store_dwordx2 v[176:177], v[96:97], off offset:1024
	global_store_dwordx2 v[176:177], v[100:101], off offset:1536
	s_add_u32 s26, s88, s26
	s_addc_u32 s27, s89, 0
	s_and_saveexec_b64 s[98:99], vcc
	global_store_dword v1, v169, s[26:27]
	s_or_b64 exec, exec, s[98:99]
	global_load_dwordx4 v[72:75], v0, s[18:19] nt
	global_load_dwordx4 v[76:79], v0, s[18:19] offset:1024 nt
	global_load_dwordx4 v[80:83], v0, s[18:19] offset:2048 nt
	global_load_dwordx4 v[84:87], v0, s[18:19] offset:3072 nt
	global_load_dwordx4 v[88:91], v0, s[20:21] nt
	global_load_dwordx4 v[92:95], v0, s[20:21] offset:1024 nt
	global_load_dwordx4 v[96:99], v0, s[20:21] offset:2048 nt
	global_load_dwordx4 v[100:103], v0, s[20:21] offset:3072 nt
	s_waitcnt vmcnt(18)
	v_mul_f32_e32 v152, v105, v105
	v_mul_f32_e32 v153, v107, v107
	v_mul_f32_e32 v154, v109, v109
	v_mul_f32_e32 v155, v111, v111
	v_mul_f32_e32 v156, v113, v113
	v_mul_f32_e32 v157, v115, v115
	v_mul_f32_e32 v158, v117, v117
	v_mul_f32_e32 v159, v119, v119
	v_fmac_f32_e32 v152, v104, v104
	v_fmac_f32_e32 v153, v106, v106
	v_fmac_f32_e32 v154, v108, v108
	v_fmac_f32_e32 v155, v110, v110
	v_fmac_f32_e32 v156, v112, v112
	v_fmac_f32_e32 v157, v114, v114
	v_fmac_f32_e32 v158, v116, v116
	v_fmac_f32_e32 v159, v118, v118
	v_add_f32_e32 v152, v152, v153
	v_add_f32_e32 v154, v154, v155
	v_add_f32_e32 v156, v156, v157
	v_add_f32_e32 v158, v158, v159
	v_add_f32_e32 v170, v152, v154
	v_add_f32_e32 v170, v170, v156
	v_add_f32_e32 v170, v170, v158
	v_mul_f32_e32 v160, v121, v121
	v_mul_f32_e32 v161, v123, v123
	v_mul_f32_e32 v162, v125, v125
	v_mul_f32_e32 v163, v127, v127
	v_mul_f32_e32 v164, v129, v129
	v_mul_f32_e32 v165, v131, v131
	v_mul_f32_e32 v166, v133, v133
	v_mul_f32_e32 v167, v135, v135
	v_fmac_f32_e32 v160, v120, v120
	v_fmac_f32_e32 v161, v122, v122
	v_fmac_f32_e32 v162, v124, v124
	v_fmac_f32_e32 v163, v126, v126
	v_fmac_f32_e32 v164, v128, v128
	v_fmac_f32_e32 v165, v130, v130
	v_fmac_f32_e32 v166, v132, v132
	v_fmac_f32_e32 v167, v134, v134
	v_add_f32_e32 v160, v160, v161
	v_add_f32_e32 v162, v162, v163
	v_add_f32_e32 v164, v164, v165
	v_add_f32_e32 v166, v166, v167
	v_add_f32_e32 v171, v160, v162
	v_add_f32_e32 v171, v171, v164
	v_add_f32_e32 v171, v171, v166
	ds_bpermute_b32 v174, v4, v170
	ds_bpermute_b32 v175, v4, v171
	s_waitcnt lgkmcnt(0)
	v_add_f32_e32 v170, v170, v174
	v_add_f32_e32 v171, v171, v175
	ds_bpermute_b32 v174, v5, v170
	ds_bpermute_b32 v175, v5, v171
	s_waitcnt lgkmcnt(0)
	v_add_f32_e32 v170, v170, v174
	v_add_f32_e32 v171, v171, v175
	ds_bpermute_b32 v174, v6, v170
	ds_bpermute_b32 v175, v6, v171
	s_waitcnt lgkmcnt(0)
	v_add_f32_e32 v170, v170, v174
	v_add_f32_e32 v171, v171, v175
	ds_bpermute_b32 v174, v7, v170
	ds_bpermute_b32 v175, v7, v171
	s_waitcnt lgkmcnt(0)
	v_add_f32_e32 v170, v170, v174
	v_add_f32_e32 v171, v171, v175
	ds_bpermute_b32 v174, v9, v170
	ds_bpermute_b32 v175, v9, v171
	s_waitcnt lgkmcnt(0)
	v_add_f32_e32 v170, v170, v174
	v_add_f32_e32 v171, v171, v175
	ds_bpermute_b32 v174, v10, v170
	ds_bpermute_b32 v175, v10, v171
	s_waitcnt lgkmcnt(0)
	v_add_f32_e32 v170, v170, v174
	v_add_f32_e32 v171, v171, v175
	v_cvt_pk_bf16_f32 v104, v104, v105
	v_cvt_pk_bf16_f32 v105, v106, v107
	v_cvt_pk_bf16_f32 v108, v108, v109
	v_cvt_pk_bf16_f32 v109, v110, v111
	v_cvt_pk_bf16_f32 v112, v112, v113
	v_cvt_pk_bf16_f32 v113, v114, v115
	v_cvt_pk_bf16_f32 v116, v116, v117
	v_cvt_pk_bf16_f32 v117, v118, v119
	s_mul_i32 s10, s66, 2
	s_add_i32 s10, s10, s0
	s_lshl_b32 s26, s10, 2
	s_lshl_b32 s10, s10, 11
	s_mov_b32 s11, 0
	v_lshl_add_u64 v[176:177], v[2:3], 0, s[10:11]
	global_store_dwordx2 v[176:177], v[104:105], off
	global_store_dwordx2 v[176:177], v[108:109], off offset:512
	global_store_dwordx2 v[176:177], v[112:113], off offset:1024
	global_store_dwordx2 v[176:177], v[116:117], off offset:1536
	s_add_u32 s26, s88, s26
	s_addc_u32 s27, s89, 0
	s_and_saveexec_b64 s[98:99], vcc
	global_store_dword v1, v170, s[26:27]
	s_or_b64 exec, exec, s[98:99]
	v_cvt_pk_bf16_f32 v120, v120, v121
	v_cvt_pk_bf16_f32 v121, v122, v123
	v_cvt_pk_bf16_f32 v124, v124, v125
	v_cvt_pk_bf16_f32 v125, v126, v127
	v_cvt_pk_bf16_f32 v128, v128, v129
	v_cvt_pk_bf16_f32 v129, v130, v131
	v_cvt_pk_bf16_f32 v132, v132, v133
	v_cvt_pk_bf16_f32 v133, v134, v135
	s_mul_i32 s10, s66, 3
	s_add_i32 s10, s10, s0
	s_lshl_b32 s26, s10, 2
	s_lshl_b32 s10, s10, 11
	s_mov_b32 s11, 0
	v_lshl_add_u64 v[176:177], v[2:3], 0, s[10:11]
	global_store_dwordx2 v[176:177], v[120:121], off
	global_store_dwordx2 v[176:177], v[124:125], off offset:512
	global_store_dwordx2 v[176:177], v[128:129], off offset:1024
	global_store_dwordx2 v[176:177], v[132:133], off offset:1536
	s_add_u32 s26, s88, s26
	s_addc_u32 s27, s89, 0
	s_and_saveexec_b64 s[98:99], vcc
	global_store_dword v1, v171, s[26:27]
	s_or_b64 exec, exec, s[98:99]
	global_load_dwordx4 v[104:107], v0, s[22:23] nt
	global_load_dwordx4 v[108:111], v0, s[22:23] offset:1024 nt
	global_load_dwordx4 v[112:115], v0, s[22:23] offset:2048 nt
	global_load_dwordx4 v[116:119], v0, s[22:23] offset:3072 nt
	global_load_dwordx4 v[120:123], v0, s[24:25] nt
	global_load_dwordx4 v[124:127], v0, s[24:25] offset:1024 nt
	global_load_dwordx4 v[128:131], v0, s[24:25] offset:2048 nt
	global_load_dwordx4 v[132:135], v0, s[24:25] offset:3072 nt
	s_waitcnt vmcnt(18)
; __device__ __forceinline__ unsigned pk2(float lo, float hi) { return pg8::cvt_pk_bf16(lo, hi); }
; __device__ __forceinline__ float wave_sum(float v) {
; #pragma unroll
;     for (int o = 1; o < 64; o <<= 1) v += __shfl_xor(v, o);
;     return v;
; }
; __device__ __forceinline__ void prologue(const Args& a, LAS unsigned char* lds, int tid, int wave, int lane) {
;     ...
;     float* ss = (float*)(ws + WS_SS); bf16_t* XB = (bf16_t*)(ws + WS_A);
;     for (int m = gw; m < MTOK; m += NGW) {
;         const float* src = (m < NTOK_P) ? a.in[I_XP] + (size_t)m * DM : a.in[I_XS] + (size_t)(m - NTOK_P) * DM;
;         f32x4 v[4]; float s = 0.f;
; #pragma unroll
;         for (int j = 0; j < 4; ++j) { v[j] = __builtin_nontemporal_load((const f32x4*)src + lane + 64 * j); s += (v[j][0] * v[j][0] + v[j][1] * v[j][1]) + (v[j][2] * v[j][2] + v[j][3] * v[j][3]); }
;         s = wave_sum(s);
; #pragma unroll
;         for (int j = 0; j < 4; ++j) { u32x2 w; w.x = pk2(v[j][0], v[j][1]); w.y = pk2(v[j][2], v[j][3]); *((u32x2*)(XB + (size_t)m * DM) + lane + 64 * j) = w; }
;         if (lane == 0) ss[m] = s;
;     }
	v_mul_f32_e32 v136, v73, v73
	v_mul_f32_e32 v137, v75, v75
	v_mul_f32_e32 v138, v77, v77
	v_mul_f32_e32 v139, v79, v79
	v_mul_f32_e32 v140, v81, v81
	v_mul_f32_e32 v141, v83, v83
	v_mul_f32_e32 v142, v85, v85
	v_mul_f32_e32 v143, v87, v87
	v_fmac_f32_e32 v136, v72, v72
	v_fmac_f32_e32 v137, v74, v74
	v_fmac_f32_e32 v138, v76, v76
	v_fmac_f32_e32 v139, v78, v78
	v_fmac_f32_e32 v140, v80, v80
	v_fmac_f32_e32 v141, v82, v82
	v_fmac_f32_e32 v142, v84, v84
	v_fmac_f32_e32 v143, v86, v86
	v_add_f32_e32 v136, v136, v137
	v_add_f32_e32 v138, v138, v139
	v_add_f32_e32 v140, v140, v141
	v_add_f32_e32 v142, v142, v143
	v_add_f32_e32 v168, v136, v138
	v_add_f32_e32 v168, v168, v140
	v_add_f32_e32 v168, v168, v142
	v_mul_f32_e32 v144, v89, v89
	v_mul_f32_e32 v145, v91, v91
	v_mul_f32_e32 v146, v93, v93
	v_mul_f32_e32 v147, v95, v95
	v_mul_f32_e32 v148, v97, v97
	v_mul_f32_e32 v149, v99, v99
	v_mul_f32_e32 v150, v101, v101
	v_mul_f32_e32 v151, v103, v103
	v_fmac_f32_e32 v144, v88, v88
	v_fmac_f32_e32 v145, v90, v90
	v_fmac_f32_e32 v146, v92, v92
	v_fmac_f32_e32 v147, v94, v94
	v_fmac_f32_e32 v148, v96, v96
	v_fmac_f32_e32 v149, v98, v98
	v_fmac_f32_e32 v150, v100, v100
	v_fmac_f32_e32 v151, v102, v102
	v_add_f32_e32 v144, v144, v145
	v_add_f32_e32 v146, v146, v147
	v_add_f32_e32 v148, v148, v149
	v_add_f32_e32 v150, v150, v151
	v_add_f32_e32 v169, v144, v146
	v_add_f32_e32 v169, v169, v148
	v_add_f32_e32 v169, v169, v150
	ds_bpermute_b32 v172, v4, v168
	ds_bpermute_b32 v173, v4, v169
	s_waitcnt lgkmcnt(0)
	v_add_f32_e32 v168, v168, v172
	v_add_f32_e32 v169, v169, v173
	ds_bpermute_b32 v172, v5, v168
	ds_bpermute_b32 v173, v5, v169
	s_waitcnt lgkmcnt(0)
	v_add_f32_e32 v168, v168, v172
	v_add_f32_e32 v169, v169, v173
	ds_bpermute_b32 v172, v6, v168
	ds_bpermute_b32 v173, v6, v169
	s_waitcnt lgkmcnt(0)
	v_add_f32_e32 v168, v168, v172
	v_add_f32_e32 v169, v169, v173
	ds_bpermute_b32 v172, v7, v168
	ds_bpermute_b32 v173, v7, v169
	s_waitcnt lgkmcnt(0)
	v_add_f32_e32 v168, v168, v172
	v_add_f32_e32 v169, v169, v173
	ds_bpermute_b32 v172, v9, v168
	ds_bpermute_b32 v173, v9, v169
	s_waitcnt lgkmcnt(0)
	v_add_f32_e32 v168, v168, v172
	v_add_f32_e32 v169, v169, v173
	ds_bpermute_b32 v172, v10, v168
	ds_bpermute_b32 v173, v10, v169
	s_waitcnt lgkmcnt(0)
	v_add_f32_e32 v168, v168, v172
	v_add_f32_e32 v169, v169, v173
	v_cvt_pk_bf16_f32 v72, v72, v73
	v_cvt_pk_bf16_f32 v73, v74, v75
	v_cvt_pk_bf16_f32 v76, v76, v77
	v_cvt_pk_bf16_f32 v77, v78, v79
	v_cvt_pk_bf16_f32 v80, v80, v81
	v_cvt_pk_bf16_f32 v81, v82, v83
	v_cvt_pk_bf16_f32 v84, v84, v85
	v_cvt_pk_bf16_f32 v85, v86, v87
	s_mul_i32 s10, s66, 4
	s_add_i32 s10, s10, s0
	s_lshl_b32 s26, s10, 2
	s_lshl_b32 s10, s10, 11
	s_mov_b32 s11, 0
	v_lshl_add_u64 v[176:177], v[2:3], 0, s[10:11]
	global_store_dwordx2 v[176:177], v[72:73], off
	global_store_dwordx2 v[176:177], v[76:77], off offset:512
	global_store_dwordx2 v[176:177], v[80:81], off offset:1024
	global_store_dwordx2 v[176:177], v[84:85], off offset:1536
	s_add_u32 s26, s88, s26
	s_addc_u32 s27, s89, 0
	s_and_saveexec_b64 s[98:99], vcc
	global_store_dword v1, v168, s[26:27]
	s_or_b64 exec, exec, s[98:99]
	v_cvt_pk_bf16_f32 v88, v88, v89
	v_cvt_pk_bf16_f32 v89, v90, v91
	v_cvt_pk_bf16_f32 v92, v92, v93
	v_cvt_pk_bf16_f32 v93, v94, v95
	v_cvt_pk_bf16_f32 v96, v96, v97
	v_cvt_pk_bf16_f32 v97, v98, v99
	v_cvt_pk_bf16_f32 v100, v100, v101
	v_cvt_pk_bf16_f32 v101, v102, v103
	s_mul_i32 s10, s66, 5
	s_add_i32 s10, s10, s0
	s_lshl_b32 s26, s10, 2
	s_lshl_b32 s10, s10, 11
	s_mov_b32 s11, 0
	v_lshl_add_u64 v[176:177], v[2:3], 0, s[10:11]
	global_store_dwordx2 v[176:177], v[88:89], off
	global_store_dwordx2 v[176:177], v[92:93], off offset:512
	global_store_dwordx2 v[176:177], v[96:97], off offset:1024
	global_store_dwordx2 v[176:177], v[100:101], off offset:1536
	s_add_u32 s26, s88, s26
	s_addc_u32 s27, s89, 0
	s_and_saveexec_b64 s[98:99], vcc
	global_store_dword v1, v169, s[26:27]
	s_or_b64 exec, exec, s[98:99]
	s_waitcnt vmcnt(10)
; __device__ __forceinline__ unsigned pk2(float lo, float hi) { return pg8::cvt_pk_bf16(lo, hi); }
; __device__ __forceinline__ float wave_sum(float v) {
; #pragma unroll
;     for (int o = 1; o < 64; o <<= 1) v += __shfl_xor(v, o);
;     return v;
; }
; __device__ __forceinline__ void prologue(const Args& a, LAS unsigned char* lds, int tid, int wave, int lane) {
;     ...
;     float* ss = (float*)(ws + WS_SS); bf16_t* XB = (bf16_t*)(ws + WS_A);
;     for (int m = gw; m < MTOK; m += NGW) {
;         const float* src = (m < NTOK_P) ? a.in[I_XP] + (size_t)m * DM : a.in[I_XS] + (size_t)(m - NTOK_P) * DM;
;         f32x4 v[4]; float s = 0.f;
; #pragma unroll
;         for (int j = 0; j < 4; ++j) { v[j] = __builtin_nontemporal_load((const f32x4*)src + lane + 64 * j); s += (v[j][0] * v[j][0] + v[j][1] * v[j][1]) + (v[j][2] * v[j][2] + v[j][3] * v[j][3]); }
;         s = wave_sum(s);
; #pragma unroll
;         for (int j = 0; j < 4; ++j) { u32x2 w; w.x = pk2(v[j][0], v[j][1]); w.y = pk2(v[j][2], v[j][3]); *((u32x2*)(XB + (size_t)m * DM) + lane + 64 * j) = w; }
;         if (lane == 0) ss[m] = s;
;     }
	v_mul_f32_e32 v152, v105, v105
	v_mul_f32_e32 v153, v107, v107
	v_mul_f32_e32 v154, v109, v109
	v_mul_f32_e32 v155, v111, v111
	v_mul_f32_e32 v156, v113, v113
	v_mul_f32_e32 v157, v115, v115
	v_mul_f32_e32 v158, v117, v117
	v_mul_f32_e32 v159, v119, v119
	v_fmac_f32_e32 v152, v104, v104
	v_fmac_f32_e32 v153, v106, v106
	v_fmac_f32_e32 v154, v108, v108
	v_fmac_f32_e32 v155, v110, v110
	v_fmac_f32_e32 v156, v112, v112
	v_fmac_f32_e32 v157, v114, v114
	v_fmac_f32_e32 v158, v116, v116
	v_fmac_f32_e32 v159, v118, v118
	v_add_f32_e32 v152, v152, v153
	v_add_f32_e32 v154, v154, v155
	v_add_f32_e32 v156, v156, v157
	v_add_f32_e32 v158, v158, v159
	v_add_f32_e32 v170, v152, v154
	v_add_f32_e32 v170, v170, v156
	v_add_f32_e32 v170, v170, v158
	v_mul_f32_e32 v160, v121, v121
	v_mul_f32_e32 v161, v123, v123
	v_mul_f32_e32 v162, v125, v125
	v_mul_f32_e32 v163, v127, v127
	v_mul_f32_e32 v164, v129, v129
	v_mul_f32_e32 v165, v131, v131
	v_mul_f32_e32 v166, v133, v133
	v_mul_f32_e32 v167, v135, v135
	v_fmac_f32_e32 v160, v120, v120
	v_fmac_f32_e32 v161, v122, v122
	v_fmac_f32_e32 v162, v124, v124
	v_fmac_f32_e32 v163, v126, v126
	v_fmac_f32_e32 v164, v128, v128
	v_fmac_f32_e32 v165, v130, v130
	v_fmac_f32_e32 v166, v132, v132
	v_fmac_f32_e32 v167, v134, v134
	v_add_f32_e32 v160, v160, v161
	v_add_f32_e32 v162, v162, v163
	v_add_f32_e32 v164, v164, v165
	v_add_f32_e32 v166, v166, v167
	v_add_f32_e32 v171, v160, v162
	v_add_f32_e32 v171, v171, v164
	v_add_f32_e32 v171, v171, v166
	ds_bpermute_b32 v174, v4, v170
	ds_bpermute_b32 v175, v4, v171
	s_waitcnt lgkmcnt(0)
	v_add_f32_e32 v170, v170, v174
	v_add_f32_e32 v171, v171, v175
	ds_bpermute_b32 v174, v5, v170
	ds_bpermute_b32 v175, v5, v171
	s_waitcnt lgkmcnt(0)
	v_add_f32_e32 v170, v170, v174
	v_add_f32_e32 v171, v171, v175
	ds_bpermute_b32 v174, v6, v170
	ds_bpermute_b32 v175, v6, v171
	s_waitcnt lgkmcnt(0)
	v_add_f32_e32 v170, v170, v174
	v_add_f32_e32 v171, v171, v175
	ds_bpermute_b32 v174, v7, v170
	ds_bpermute_b32 v175, v7, v171
	s_waitcnt lgkmcnt(0)
	v_add_f32_e32 v170, v170, v174
	v_add_f32_e32 v171, v171, v175
	ds_bpermute_b32 v174, v9, v170
	ds_bpermute_b32 v175, v9, v171
	s_waitcnt lgkmcnt(0)
	v_add_f32_e32 v170, v170, v174
	v_add_f32_e32 v171, v171, v175
	ds_bpermute_b32 v174, v10, v170
	ds_bpermute_b32 v175, v10, v171
	s_waitcnt lgkmcnt(0)
	v_add_f32_e32 v170, v170, v174
	v_add_f32_e32 v171, v171, v175
	v_cvt_pk_bf16_f32 v104, v104, v105
	v_cvt_pk_bf16_f32 v105, v106, v107
	v_cvt_pk_bf16_f32 v108, v108, v109
	v_cvt_pk_bf16_f32 v109, v110, v111
	v_cvt_pk_bf16_f32 v112, v112, v113
	v_cvt_pk_bf16_f32 v113, v114, v115
	v_cvt_pk_bf16_f32 v116, v116, v117
	v_cvt_pk_bf16_f32 v117, v118, v119
	s_mul_i32 s10, s66, 6
	s_add_i32 s10, s10, s0
	s_lshl_b32 s26, s10, 2
	s_lshl_b32 s10, s10, 11
	s_mov_b32 s11, 0
	v_lshl_add_u64 v[176:177], v[2:3], 0, s[10:11]
	global_store_dwordx2 v[176:177], v[104:105], off
	global_store_dwordx2 v[176:177], v[108:109], off offset:512
	global_store_dwordx2 v[176:177], v[112:113], off offset:1024
	global_store_dwordx2 v[176:177], v[116:117], off offset:1536
	s_add_u32 s26, s88, s26
	s_addc_u32 s27, s89, 0
	s_and_saveexec_b64 s[98:99], vcc
	global_store_dword v1, v170, s[26:27]
	s_or_b64 exec, exec, s[98:99]
	v_cvt_pk_bf16_f32 v120, v120, v121
	v_cvt_pk_bf16_f32 v121, v122, v123
	v_cvt_pk_bf16_f32 v124, v124, v125
	v_cvt_pk_bf16_f32 v125, v126, v127
	v_cvt_pk_bf16_f32 v128, v128, v129
	v_cvt_pk_bf16_f32 v129, v130, v131
	v_cvt_pk_bf16_f32 v132, v132, v133
	v_cvt_pk_bf16_f32 v133, v134, v135
	s_mul_i32 s10, s66, 7
	s_add_i32 s10, s10, s0
	s_lshl_b32 s26, s10, 2
	s_lshl_b32 s10, s10, 11
	s_mov_b32 s11, 0
	v_lshl_add_u64 v[176:177], v[2:3], 0, s[10:11]
	global_store_dwordx2 v[176:177], v[120:121], off
	global_store_dwordx2 v[176:177], v[124:125], off offset:512
	global_store_dwordx2 v[176:177], v[128:129], off offset:1024
	global_store_dwordx2 v[176:177], v[132:133], off offset:1536
	s_add_u32 s26, s88, s26
	s_addc_u32 s27, s89, 0
	s_and_saveexec_b64 s[98:99], vcc
	global_store_dword v1, v171, s[26:27]
	s_or_b64 exec, exec, s[98:99]
	s_lshl_b64 s[10:11], s[66:67], 3
	s_add_u32 s0, s0, s10
	s_addc_u32 s1, s1, s11
	s_lshl_b64 s[10:11], s[8:9], 3
	s_add_u32 s6, s6, s10
	s_addc_u32 s7, s7, s11
	s_cmpk_gt_i32 s0, 0x41ff
	s_cbranch_scc1 .LBB0_136
	s_branch .LBB0_132

; __device__ __forceinline__ float bf2f(unsigned short b) { return __uint_as_float(((unsigned)b) << 16); }
; __device__ __forceinline__ unsigned short f2bf(float f) { return (unsigned short)(pg8::cvt_pk_bf16(f, 0.f) & 0xffffu); }
; __device__ __forceinline__ void attn_sample_unit(const Args& a, LAS unsigned char* lds, int l, int b, int kvh, int tid) {
;     ...
;         if (tid < 256) { const int t2 = tid >> 6, d = tid & 63; const bf16_t* zr = Z + (zrow0 + t2) * INC + kvh * 64 + d;
;             const float kr = bf2f(zr[ZK]), vr = bf2f(zr[ZV]); const float sq = wave_sum(kr * kr); const float kn = kr * rsqrtf(sq * (1.f / 64.f) + EPS) * gk[d];
;             Ks[(WIN + t2) * KST + d] = f2bf(kn); Vt[d * VST + WIN + t2] = zr[ZV]; ko[(size_t)(WIN - DEC_T + t2) * 128 + d] = kn; vo[(size_t)(WIN - DEC_T + t2) * 128 + d] = vr; }
.LBB0_607:
	s_or_b64 exec, exec, s[8:9]
	s_movk_i32 s8, 0x100
	v_cmp_gt_i32_e32 vcc, s8, v77
	s_and_saveexec_b64 s[8:9], vcc
	s_cbranch_execz .LBB0_609
	v_ashrrev_i32_e32 v28, 6, v77
	v_ashrrev_i32_e32 v29, 31, v28
	v_lshl_add_u64 v[30:31], s[10:11], 0, v[28:29]
	v_mov_b64_e32 v[32:33], s[48:49]
	v_mad_u64_u32 v[32:33], s[10:11], v30, s87, v[32:33]
	v_mad_i32_i24 v33, v31, s87, v33
	s_lshl_b32 s26, s17, 1
	v_lshl_add_u64 v[30:31], v[32:33], 0, s[26:27]
	v_lshlrev_b32_e32 v0, 1, v67
	v_lshl_add_u64 v[30:31], v[30:31], 0, v[0:1]
	global_load_ushort v32, v[30:31], off offset:1024
	global_load_ushort v37, v[30:31], off offset:1280
	v_lshlrev_b32_e32 v38, 2, v67
	global_load_dword v39, v38, s[42:43]
	v_and_b32_e32 v35, 64, v216
	v_add_u32_e32 v35, 64, v35
	v_xor_b32_e32 v36, 1, v216
	v_cmp_lt_i32_e32 vcc, v36, v35
	s_mov_b64 s[10:11], 0xf800
	s_waitcnt vmcnt(0)
	v_lshlrev_b32_e32 v33, 16, v32
	v_cndmask_b32_e32 v36, v216, v36, vcc
	v_mul_f32_e32 v34, v33, v33
	v_lshlrev_b32_e32 v36, 2, v36
	ds_bpermute_b32 v34, v36, v34
	v_xor_b32_e32 v36, 2, v216
	v_cmp_lt_i32_e32 vcc, v36, v35
	s_waitcnt lgkmcnt(0)
	v_fmac_f32_e32 v34, v33, v33
	v_cndmask_b32_e32 v36, v216, v36, vcc
	v_lshlrev_b32_e32 v36, 2, v36
	ds_bpermute_b32 v36, v36, v34
	s_waitcnt lgkmcnt(0)
	v_add_f32_e32 v34, v34, v36
	v_xor_b32_e32 v36, 4, v216
	v_cmp_lt_i32_e32 vcc, v36, v35
	v_lshlrev_b32_e32 v32, 16, v37
	v_cndmask_b32_e32 v36, v216, v36, vcc
	v_lshlrev_b32_e32 v36, 2, v36
	ds_bpermute_b32 v36, v36, v34
	s_waitcnt lgkmcnt(0)
	v_add_f32_e32 v34, v34, v36
	v_xor_b32_e32 v36, 8, v216
	v_cmp_lt_i32_e32 vcc, v36, v35
	s_nop 1
	v_cndmask_b32_e32 v36, v216, v36, vcc
	v_lshlrev_b32_e32 v36, 2, v36
	ds_bpermute_b32 v36, v36, v34
	s_waitcnt lgkmcnt(0)
	v_add_f32_e32 v34, v34, v36
	v_xor_b32_e32 v36, 16, v216
	v_cmp_lt_i32_e32 vcc, v36, v35
	s_nop 1
	v_cndmask_b32_e32 v36, v216, v36, vcc
	v_lshlrev_b32_e32 v36, 2, v36
	ds_bpermute_b32 v36, v36, v34
	s_waitcnt lgkmcnt(0)
	v_add_f32_e32 v34, v34, v36
	v_xor_b32_e32 v36, 32, v216
	v_cmp_lt_i32_e32 vcc, v36, v35
	s_nop 1
	v_cndmask_b32_e32 v35, v216, v36, vcc
	v_lshlrev_b32_e32 v35, 2, v35
	ds_bpermute_b32 v35, v35, v34
	v_mul_lo_u32 v36, v28, s88
	v_add3_u32 v0, 0, v36, v0
	s_waitcnt lgkmcnt(0)
	v_add_f32_e32 v34, v34, v35
	v_fmamk_f32 v34, v34, 0x3c800000, v185
	v_cmp_gt_f32_e32 vcc, s86, v34
	v_mul_f32_e32 v35, 0x4b800000, v34
	s_nop 0
	v_cndmask_b32_e32 v34, v34, v35, vcc
	v_rsq_f32_e32 v34, v34
	s_nop 0
	v_mul_f32_e32 v35, 0x45800000, v34
	v_cndmask_b32_e32 v34, v34, v35, vcc
	v_mul_f32_e32 v33, v34, v33
	v_lshlrev_b32_e32 v34, 2, v67
	v_mul_f32_e32 v33, v39, v33
	v_cvt_pk_bf16_f32 v35, v33, v1
	ds_write_b16 v0, v35 offset:18432
	v_mov_b32_e32 v0, v37
	v_lshlrev_b32_e32 v31, 1, v28
	v_lshlrev_b64 v[28:29], 9, v[28:29]
	v_mul_u32_u24_e32 v30, 0x160, v67
	v_or_b32_e32 v28, v28, v34
	v_add3_u32 v30, 0, v30, v31
	v_lshl_add_u64 v[28:29], v[28:29], 0, s[10:11]
	ds_write_b16 v30, v0 offset:23296
	v_lshl_add_u64 v[30:31], s[6:7], 0, v[28:29]
	v_lshl_add_u64 v[28:29], s[0:1], 0, v[28:29]
	global_store_dword v[30:31], v33, off
	global_store_dword v[28:29], v32, off
